# gdn_prep: q|k row loads of all 4 conv taps issued at the job top into dead registers; conv-weight load no longer waited before beta/g stage
# speedup vs baseline: 1.0105x; 1.0105x over previous
; #define GAS __attribute__((address_space(1)))
; #define LAS __attribute__((address_space(3)))
; DI float fexp(float x) { return __builtin_amdgcn_exp2f(x * 1.4426950408889634f); }
; DI float sigm(float x) { return frcp(1.f + fexp(-x)); }
; DI float softplus(float x) { return fmaxf(x, 0.f) + flog(1.f + fexp(-fabsf(x))); }
;     ...
;     if (tid < 384) { const int j = tid / 96, i96 = tid % 96, seg = i96 >> 5, c4 = (i96 & 31) * 4;
;         const f32x4 cwv = *(const GAS f32x4*)(F.in[15] + ((size_t)layer * 4 + j) * 2304 + seg * 768 + h * 128 + c4);
;         *(LAS f32x4*)(L + gp::CW + (j * 384 + seg * 128 + c4) * 4) = cwv; }
;     if (wave == 0) {
;         const float* pba = PBA + (m0 + lane) * 16;
;         const float beta = sigm(pba[h]);
;         float g = -fexp(F.in[16][layer * 6 + h]) * softplus(pba[6 + h] + F.in[17][layer * 6 + h]);
; #pragma unroll
;         for (int o = 1; o < 64; o <<= 1) { const float v = __shfl_up(g, o); if (lane >= o) g += v; }
;         const float blast = __shfl(g, 63);
;         BETA[lane] = beta; BC[lane] = g;
;         if (lane == 0) { BC[64] = blast; ((float*)(F.ws + WS_GE))[cidx] = fexp(blast); }
;     ...
;         v4u xq[4][4];
; #pragma unroll
;         for (int j = 0; j < 4; ++j) {
;             const int tt = t0 + t - 3 + j;
;             if (tt >= 0) { const bf16* src = P + ((size_t)b * SEQ + tt) * NP + pcol;
; #pragma unroll
;                 for (int q4 = 0; q4 < 4; ++q4) xq[j][q4] = *(const GAS v4u*)(src + 8 * q4); }
;         }
.LBB0_715:
	s_ashr_i32 s62, s47, 6
	s_mul_hi_i32 s2, s62, 0x2aaaaaab
	s_lshr_b32 s48, s2, 31
	s_add_i32 s64, s2, s48
	s_mul_i32 s2, s64, 6
	s_sub_i32 s60, s62, s2
	s_and_saveexec_b64 s[66:67], s[40:41]
	s_cbranch_execz .LBB0_717
	s_load_dwordx2 s[48:49], s[82:83], 0x78
	v_mov_b32_e32 v75, v97
	s_waitcnt lgkmcnt(0)
	v_lshl_add_u64 v[0:1], s[48:49], 0, v[64:65]
	s_lshl_b32 s48, s60, 7
	v_lshl_add_u64 v[0:1], v[66:67], 2, v[0:1]
	s_ashr_i32 s49, s48, 31
	v_lshl_add_u64 v[0:1], s[48:49], 2, v[0:1]
	v_lshl_add_u64 v[0:1], v[0:1], 0, v[74:75]
	global_load_dwordx4 v[238:241], v[0:1], off
.LBB0_717:
	s_or_b64 exec, exec, s[66:67]
	s_ashr_i32 s63, s62, 31
	s_and_b32 s48, s47, 63
	s_ashr_i32 s65, s64, 31
	s_lshl_b64 s[76:77], s[62:63], 6
	s_lshl_b32 s2, s48, 6
	s_lshl_b64 s[86:87], s[64:65], 12
	s_lshl_b32 s100, s60, 7
	v_add_u32_e32 v98, s100, v137
	v_mov_b32_e32 v99, v97
	v_add_u32_e32 v233, s2, v132
	v_lshl_add_u64 v[62:63], v[98:99], 1, s[0:1]
	v_add_u32_e32 v242, s86, v233
	v_cmp_lt_i32_e32 vcc, -1, v233
	s_and_saveexec_b64 s[100:101], vcc
	v_mad_u64_u32 v[250:251], vcc, v242, s97, v[62:63]
	global_load_dwordx4 v[54:57], v[250:251], off offset:48
	global_load_dwordx4 v[58:61], v[250:251], off offset:32
	global_load_dwordx4 v[102:105], v[250:251], off offset:16
	global_load_dwordx4 v[106:109], v[250:251], off
	s_mov_b64 exec, s[100:101]
	v_add_u32_e32 v242, 1, v242
	v_cmp_lt_i32_e32 vcc, -2, v233
	s_and_saveexec_b64 s[100:101], vcc
	v_mad_u64_u32 v[250:251], vcc, v242, s97, v[62:63]
	global_load_dwordx4 v[110:113], v[250:251], off offset:48
	global_load_dwordx4 v[114:117], v[250:251], off offset:32
	global_load_dwordx4 v[118:121], v[250:251], off offset:16
	global_load_dwordx4 v[122:125], v[250:251], off
	s_mov_b64 exec, s[100:101]
	v_add_u32_e32 v242, 1, v242
	v_cmp_lt_i32_e32 vcc, -3, v233
	s_and_saveexec_b64 s[100:101], vcc
	v_mad_u64_u32 v[250:251], vcc, v242, s97, v[62:63]
	global_load_dwordx4 v[126:129], v[250:251], off offset:48
	global_load_dwordx4 v[202:205], v[250:251], off offset:32
	global_load_dwordx4 v[206:209], v[250:251], off offset:16
	global_load_dwordx4 v[210:213], v[250:251], off
	s_mov_b64 exec, s[100:101]
	v_add_u32_e32 v242, 1, v242
	v_cmp_lt_i32_e32 vcc, -4, v233
	s_and_saveexec_b64 s[100:101], vcc
	v_mad_u64_u32 v[250:251], vcc, v242, s97, v[62:63]
	global_load_dwordx4 v[214:217], v[250:251], off offset:48
	global_load_dwordx4 v[218:221], v[250:251], off offset:32
	global_load_dwordx4 v[222:225], v[250:251], off offset:16
	global_load_dwordx4 v[234:237], v[250:251], off
	s_mov_b64 exec, s[100:101]
	s_andn2_b64 vcc, exec, s[80:81]
	s_or_b32 s76, s76, s48
	s_cbranch_vccnz .LBB0_721
	s_load_dwordx4 s[64:67], s[82:83], 0x80
	v_readlane_b32 s48, v255, 17
	s_mul_i32 s48, s48, 6
	s_add_i32 s48, s60, s48
	s_ashr_i32 s49, s48, 31
	v_or_b32_e32 v0, s2, v71
	s_ashr_i32 s61, s60, 31
	s_lshl_b64 s[48:49], s[48:49], 2
	v_or_b32_e32 v0, s86, v0
	v_mov_b32_e32 v1, s87
	s_waitcnt lgkmcnt(0)
	s_add_u32 s62, s64, s48
	v_lshlrev_b64 v[0:1], 6, v[0:1]
	s_addc_u32 s63, s65, s49
	v_lshl_add_u64 v[0:1], s[78:79], 0, v[0:1]
	s_add_u32 s48, s66, s48
	v_lshl_add_u64 v[0:1], s[60:61], 2, v[0:1]
	s_addc_u32 s49, s67, s49
	flat_load_dword v2, v[0:1]
	global_load_dword v3, v97, s[62:63]
	v_and_b32_e32 v4, 64, v228
	flat_load_dword v0, v[0:1] offset:24
	v_add_u32_e32 v5, -1, v228
	global_load_dword v1, v97, s[48:49]
	s_mov_b32 s48, 0xbfb8aa3b
	v_cmp_lt_i32_e32 vcc, v5, v4
	s_waitcnt vmcnt(0) lgkmcnt(0)
	v_mul_f32_e32 v2, 0xbfb8aa3b, v2
	v_mul_f32_e32 v3, 0x3fb8aa3b, v3
	v_exp_f32_e32 v3, v3
	v_cndmask_b32_e32 v5, v5, v228, vcc
	v_lshlrev_b32_e32 v5, 2, v5
	v_add_f32_e32 v0, v0, v1
	v_max_f32_e32 v1, 0, v0
	v_mul_f32_e64 v0, |v0|, s48
	v_exp_f32_e32 v0, v0
	v_readlane_b32 s48, v255, 21
	v_readlane_b32 s49, v255, 22
	v_exp_f32_e32 v2, v2
	v_add_f32_e32 v0, 1.0, v0
	v_log_f32_e32 v0, v0
	v_add_f32_e32 v2, 1.0, v2
	v_rcp_f32_e32 v2, v2
	v_fmac_f32_e32 v1, 0x3f317218, v0
	v_mul_f32_e64 v0, v1, -v3
	ds_bpermute_b32 v5, v5, v0
	s_waitcnt lgkmcnt(0)
	v_fma_f32 v1, v1, -v3, v5
	v_cndmask_b32_e64 v0, v1, v0, s[42:43]
	v_add_u32_e32 v1, -2, v228
	v_cmp_lt_i32_e32 vcc, v1, v4
	s_nop 1
	v_cndmask_b32_e32 v1, v1, v228, vcc
	v_lshlrev_b32_e32 v1, 2, v1
	ds_bpermute_b32 v1, v1, v0
	s_waitcnt lgkmcnt(0)
	v_add_f32_e32 v1, v0, v1
	v_cndmask_b32_e64 v0, v1, v0, s[48:49]
	v_add_u32_e32 v1, -4, v228
	v_cmp_lt_i32_e32 vcc, v1, v4
	v_readlane_b32 s48, v255, 23
	v_readlane_b32 s49, v255, 24
	v_cndmask_b32_e32 v1, v1, v228, vcc
	v_lshlrev_b32_e32 v1, 2, v1
	ds_bpermute_b32 v1, v1, v0
	s_waitcnt lgkmcnt(0)
	v_add_f32_e32 v1, v0, v1
	v_cndmask_b32_e64 v0, v1, v0, s[48:49]
	v_add_u32_e32 v1, -8, v228
	v_cmp_lt_i32_e32 vcc, v1, v4
	v_readlane_b32 s48, v255, 25
	v_readlane_b32 s49, v255, 26
	v_cndmask_b32_e32 v1, v1, v228, vcc
	v_lshlrev_b32_e32 v1, 2, v1
	ds_bpermute_b32 v1, v1, v0
	s_waitcnt lgkmcnt(0)
	v_add_f32_e32 v1, v0, v1
	v_cndmask_b32_e64 v0, v1, v0, s[48:49]
	v_add_u32_e32 v1, -16, v228
	v_cmp_lt_i32_e32 vcc, v1, v4
	v_readlane_b32 s48, v255, 27
	v_readlane_b32 s49, v255, 28
	v_cndmask_b32_e32 v1, v1, v228, vcc
	v_lshlrev_b32_e32 v1, 2, v1
	ds_bpermute_b32 v1, v1, v0
	s_waitcnt lgkmcnt(0)
	v_add_f32_e32 v1, v0, v1
	v_cndmask_b32_e64 v0, v1, v0, s[48:49]
	v_subrev_u32_e32 v1, 32, v228
	v_cmp_lt_i32_e32 vcc, v1, v4
	s_nop 1
	v_cndmask_b32_e32 v1, v1, v228, vcc
	v_lshlrev_b32_e32 v1, 2, v1
	ds_bpermute_b32 v1, v1, v0
	s_waitcnt lgkmcnt(0)
	v_add_f32_e32 v1, v0, v1
	v_cndmask_b32_e64 v1, v1, v0, s[52:53]
	v_bfrev_b32_e32 v0, 0.5
	v_lshl_or_b32 v0, v228, 2, v0
	ds_bpermute_b32 v0, v0, v1
	ds_write_b32 v73, v2
	ds_write_b32 v101, v1
	s_and_saveexec_b64 s[62:63], s[42:43]
	s_cbranch_execz .LBB0_720
	s_lshl_b64 s[48:49], s[76:77], 2
	v_readlane_b32 s50, v255, 29
	s_waitcnt lgkmcnt(2)
	v_mul_f32_e32 v1, 0x3fb8aa3b, v0
	s_add_u32 s48, s50, s48
	v_readlane_b32 s50, v255, 30
	v_exp_f32_e32 v2, v1
	s_addc_u32 s49, s50, s49
	v_readlane_b32 s50, v255, 1
	s_nop 1
	v_mov_b32_e32 v1, s50
	ds_write_b32 v1, v0
	v_mov_b64_e32 v[0:1], s[48:49]
	flat_store_dword v[0:1], v2

; #define GAS __attribute__((address_space(1)))
; #define LAS __attribute__((address_space(3)))
; #define LDS_WAIT() asm volatile("s_waitcnt lgkmcnt(0)" ::: "memory")
; DI float fexp(float x) { return __builtin_amdgcn_exp2f(x * 1.4426950408889634f); }
; DI float sigm(float x) { return frcp(1.f + fexp(-x)); }
; DI float softplus(float x) { return fmaxf(x, 0.f) + flog(1.f + fexp(-fabsf(x))); }
;     ...
;         *(LAS f32x4*)(L + gp::CW + (j * 384 + seg * 128 + c4) * 4) = cwv; }
;     if (wave == 0) {
;         const float* pba = PBA + (m0 + lane) * 16;
;         const float beta = sigm(pba[h]);
;         float g = -fexp(F.in[16][layer * 6 + h]) * softplus(pba[6 + h] + F.in[17][layer * 6 + h]);
; #pragma unroll
;         for (int o = 1; o < 64; o <<= 1) { const float v = __shfl_up(g, o); if (lane >= o) g += v; }
;         const float blast = __shfl(g, 63);
;         BETA[lane] = beta; BC[lane] = g;
;         if (lane == 0) { BC[64] = blast; ((float*)(F.ws + WS_GE))[cidx] = fexp(blast); }
;     }
;     LDS_WAIT(); __syncthreads();
;     const float blast = BC[64];
;         const int t2 = tid >> 3, c02 = 16 * (tid & 7);
;         const int pcol2 = PC_V + h * 128 + c02, wch2 = 1536 + h * 128 + c02;
;         float av[16];
; #pragma unroll
;         for (int c = 0; c < 16; ++c) av[c] = 0.f;
;         v4u xv[4][2];
; #pragma unroll
;         for (int j = 0; j < 4; ++j) {
;             const int tt = t0 + t2 - 3 + j;
;             if (tt >= 0) { const bf16* src = P + ((size_t)b * SEQ + tt) * NP + pcol2; xv[j][0] = *(const GAS v4u*)src; xv[j][1] = *(const GAS v4u*)(src + 8); }
.LBB0_721:
	s_and_saveexec_b64 s[100:101], s[40:41]
	s_waitcnt vmcnt(16)
	ds_write_b128 v192, v[238:241]
	s_mov_b64 exec, s[100:101]
	v_readlane_b32 s48, v255, 1
	s_waitcnt lgkmcnt(0)
	s_waitcnt lgkmcnt(0)
	s_barrier
	v_mov_b32_e32 v0, s48
	ds_read_b32 v75, v0
	s_lshl_b32 s48, s60, 7
	v_add_u32_e32 v96, s48, v131
	v_add_u32_e32 v32, s2, v132
	v_lshl_add_u64 v[2:3], v[96:97], 1, s[0:1]
	v_cmp_lt_i32_e64 s[70:71], -1, v32
	s_and_saveexec_b64 s[60:61], s[70:71]
	s_cbranch_execz .LBB0_723
	v_mov_b32_e32 v33, v97
	v_lshl_add_u64 v[0:1], s[86:87], 0, v[32:33]
	v_mad_u64_u32 v[4:5], s[62:63], v0, s97, v[2:3]
	v_mad_i32_i24 v5, v1, s97, v5
	global_load_dwordx4 v[24:27], v[4:5], off offset:16
	global_load_dwordx4 v[28:31], v[4:5], off

; #define GAS __attribute__((address_space(1)))
; #define LAS __attribute__((address_space(3)))
; DI float bflo(unsigned w) { return __uint_as_float(w << 16); }
; DI float bfhi(unsigned w) { return __uint_as_float(w & 0xffff0000u); }
;     ...
;         v4u xq[4][4];
; #pragma unroll
;         for (int j = 0; j < 4; ++j) {
;             const int tt = t0 + t - 3 + j;
;             if (tt >= 0) { const bf16* src = P + ((size_t)b * SEQ + tt) * NP + pcol;
; #pragma unroll
;                 for (int q4 = 0; q4 < 4; ++q4) xq[j][q4] = *(const GAS v4u*)(src + 8 * q4); }
;         }
; #pragma unroll
;         for (int j = 0; j < 4; ++j) {
;             const int tt = t0 + t - 3 + j;
;             if (tt >= 0) {
;                 const LAS float* wp = (const LAS float*)(L + gp::CW) + j * 384 + isk * 128 + c0;
; #pragma unroll
;                 for (int q4 = 0; q4 < 4; ++q4) {
;                     const v4u x = xq[j][q4]; const f32x4 w0 = *(const LAS f32x4*)(wp + 8 * q4), w1 = *(const LAS f32x4*)(wp + 8 * q4 + 4);
;                     a[8 * q4 + 0] += bflo(x.x) * w0.x; a[8 * q4 + 1] += bfhi(x.x) * w0.y; a[8 * q4 + 2] += bflo(x.y) * w0.z; a[8 * q4 + 3] += bfhi(x.y) * w0.w;
;                     a[8 * q4 + 4] += bflo(x.z) * w1.x; a[8 * q4 + 5] += bfhi(x.z) * w1.y; a[8 * q4 + 6] += bflo(x.w) * w1.z; a[8 * q4 + 7] += bfhi(x.w) * w1.w;
;                 }
;             }
;         }
.LBB0_737:
	s_or_b64 exec, exec, s[72:73]
	v_add_u32_e32 v96, s48, v137
	s_waitcnt vmcnt(0)
	v_mov_b32_e32 v93, v97
	v_mov_b32_e32 v95, v97
	v_mov_b64_e32 v[48:49], v[54:55]
	v_mov_b64_e32 v[50:51], v[56:57]
	v_mov_b64_e32 v[52:53], v[58:59]
	v_mov_b64_e32 v[54:55], v[60:61]
	v_mov_b64_e32 v[56:57], v[102:103]
	v_mov_b64_e32 v[58:59], v[104:105]
	v_mov_b64_e32 v[60:61], v[106:107]
	v_mov_b64_e32 v[62:63], v[108:109]
	v_mov_b64_e32 v[32:33], v[110:111]
	v_mov_b64_e32 v[34:35], v[112:113]
	v_mov_b64_e32 v[36:37], v[114:115]
	v_mov_b64_e32 v[38:39], v[116:117]
	v_mov_b64_e32 v[40:41], v[118:119]
	v_mov_b64_e32 v[42:43], v[120:121]
	v_mov_b64_e32 v[44:45], v[122:123]
	v_mov_b64_e32 v[46:47], v[124:125]
	v_mov_b64_e32 v[16:17], v[126:127]
	v_mov_b64_e32 v[18:19], v[128:129]
	v_mov_b64_e32 v[20:21], v[202:203]
	v_mov_b64_e32 v[22:23], v[204:205]
	v_mov_b64_e32 v[24:25], v[206:207]
	v_mov_b64_e32 v[26:27], v[208:209]
	v_mov_b64_e32 v[28:29], v[210:211]
	v_mov_b64_e32 v[30:31], v[212:213]
	v_mov_b64_e32 v[0:1], v[214:215]
	v_mov_b64_e32 v[2:3], v[216:217]
	v_mov_b64_e32 v[4:5], v[218:219]
	v_mov_b64_e32 v[6:7], v[220:221]
	v_mov_b64_e32 v[8:9], v[222:223]
	v_mov_b64_e32 v[10:11], v[224:225]
	v_mov_b64_e32 v[12:13], v[234:235]
	v_mov_b64_e32 v[14:15], v[236:237]
	v_mov_b32_e32 v128, 0
	v_mov_b32_e32 v129, 0
	v_mov_b32_e32 v124, 0
	v_mov_b32_e32 v125, 0
	v_mov_b32_e32 v122, 0
	v_mov_b32_e32 v123, v128
	v_mov_b32_e32 v118, v128
	v_mov_b32_e32 v119, v128
	v_mov_b32_e32 v120, v128
	v_mov_b32_e32 v121, v128
	v_mov_b32_e32 v116, v128
	v_mov_b32_e32 v117, v128
	v_mov_b32_e32 v112, v128
	v_mov_b32_e32 v113, v128
	v_mov_b32_e32 v114, v128
	v_mov_b32_e32 v115, v128
	v_mov_b32_e32 v110, v128
	v_mov_b32_e32 v111, v128
	v_mov_b32_e32 v106, v128
	v_mov_b32_e32 v107, v128
	v_mov_b32_e32 v108, v128
	v_mov_b32_e32 v109, v128
	v_mov_b32_e32 v104, v128
	v_mov_b32_e32 v105, v128
	v_mov_b32_e32 v98, v128
	v_mov_b32_e32 v99, v128
	v_mov_b32_e32 v102, v128
	v_mov_b32_e32 v103, v128
	v_mov_b32_e32 v94, v128
	v_mov_b32_e32 v95, v128
	v_mov_b32_e32 v92, v128
	v_mov_b32_e32 v93, v128
	v_mov_b32_e32 v126, 0
	v_mov_b32_e32 v127, 0
	s_and_saveexec_b64 s[66:67], s[64:65]
	s_cbranch_execz .LBB0_749
	ds_read_b128 v[92:95], v138
	ds_read_b128 v[102:105], v138 offset:16
	ds_read_b128 v[106:109], v138 offset:32
	ds_read_b128 v[126:129], v138 offset:48
	s_waitcnt vmcnt(0)
	v_lshlrev_b32_e32 v98, 16, v60
	v_and_b32_e32 v99, 0xffff0000, v60
	v_lshlrev_b32_e32 v60, 16, v61
	v_and_b32_e32 v61, 0xffff0000, v61
	s_waitcnt lgkmcnt(3)
	v_pk_fma_f32 v[122:123], v[94:95], v[60:61], 0 op_sel_hi:[1,1,0]
	v_lshlrev_b32_e32 v60, 16, v62
	v_and_b32_e32 v61, 0xffff0000, v62
	s_waitcnt lgkmcnt(2)
	v_pk_fma_f32 v[118:119], v[102:103], v[60:61], 0 op_sel_hi:[1,1,0]
	v_lshlrev_b32_e32 v60, 16, v63
	v_and_b32_e32 v61, 0xffff0000, v63
	v_pk_fma_f32 v[120:121], v[104:105], v[60:61], 0 op_sel_hi:[1,1,0]
	v_lshlrev_b32_e32 v60, 16, v56
	v_and_b32_e32 v61, 0xffff0000, v56
	v_lshlrev_b32_e32 v56, 16, v57
	v_and_b32_e32 v57, 0xffff0000, v57
	s_waitcnt lgkmcnt(1)
	v_pk_fma_f32 v[112:113], v[108:109], v[56:57], 0 op_sel_hi:[1,1,0]
	v_lshlrev_b32_e32 v56, 16, v58
	v_and_b32_e32 v57, 0xffff0000, v58
	v_pk_fma_f32 v[116:117], v[106:107], v[60:61], 0 op_sel_hi:[1,1,0]
	s_waitcnt lgkmcnt(0)
	v_pk_fma_f32 v[114:115], v[126:127], v[56:57], 0 op_sel_hi:[1,1,0]
	v_lshlrev_b32_e32 v60, 16, v59
	v_and_b32_e32 v61, 0xffff0000, v59
	ds_read_b128 v[56:59], v138 offset:64
	v_pk_fma_f32 v[110:111], v[128:129], v[60:61], 0 op_sel_hi:[1,1,0]
	ds_read_b128 v[60:63], v138 offset:80
	v_pk_fma_f32 v[124:125], v[92:93], v[98:99], 0 op_sel_hi:[1,1,0]
	v_lshlrev_b32_e32 v92, 16, v52
	v_and_b32_e32 v93, 0xffff0000, v52
	v_lshlrev_b32_e32 v52, 16, v53
	v_and_b32_e32 v53, 0xffff0000, v53
	s_waitcnt lgkmcnt(1)
	v_pk_fma_f32 v[108:109], v[58:59], v[52:53], 0 op_sel_hi:[1,1,0]
	v_lshlrev_b32_e32 v52, 16, v54
	v_and_b32_e32 v53, 0xffff0000, v54
	v_pk_fma_f32 v[106:107], v[56:57], v[92:93], 0 op_sel_hi:[1,1,0]
	s_waitcnt lgkmcnt(0)
	v_pk_fma_f32 v[104:105], v[60:61], v[52:53], 0 op_sel_hi:[1,1,0]
	v_lshlrev_b32_e32 v56, 16, v55
	v_and_b32_e32 v57, 0xffff0000, v55
	ds_read_b128 v[52:55], v138 offset:96
	v_pk_fma_f32 v[98:99], v[62:63], v[56:57], 0 op_sel_hi:[1,1,0]
	ds_read_b128 v[56:59], v138 offset:112
	v_lshlrev_b32_e32 v60, 16, v48
	v_and_b32_e32 v61, 0xffff0000, v48
	v_lshlrev_b32_e32 v48, 16, v49
	v_and_b32_e32 v49, 0xffff0000, v49
	s_waitcnt lgkmcnt(1)
	v_pk_fma_f32 v[94:95], v[54:55], v[48:49], 0 op_sel_hi:[1,1,0]
	v_lshlrev_b32_e32 v48, 16, v50
	v_and_b32_e32 v49, 0xffff0000, v50
	s_waitcnt lgkmcnt(0)
	v_pk_fma_f32 v[92:93], v[56:57], v[48:49], 0 op_sel_hi:[1,1,0]
	v_lshlrev_b32_e32 v48, 16, v51
	v_and_b32_e32 v49, 0xffff0000, v51
	v_pk_fma_f32 v[128:129], v[58:59], v[48:49], 0 op_sel_hi:[1,1,0]
	v_pk_fma_f32 v[102:103], v[52:53], v[60:61], 0 op_sel_hi:[1,1,0]
	v_mov_b32_e32 v126, v128
	v_mov_b32_e32 v127, v129
	s_or_b64 exec, exec, s[66:67]
	s_and_saveexec_b64 s[64:65], s[62:63]
	s_cbranch_execnz .LBB0_750
